# deferred weight transposes now loop over block ids (any grid size), P3a sample-row small GEMM with all operand loads in flight first; code placement padded by 4 s_nop before the layer loop
# baseline (speedup 1.0000x reference)
; __device__ __forceinline__ void xcd_barrier(const XcdBarrier& b) {
;     ...
;     }
;     __syncthreads();
; }
; __global__ void __launch_bounds__(512, 2) fwd(Args a) {
;     ...
;     for (int L = 0; L < DEPTH; ++L) {
.LBB0_234:
	s_or_b64 exec, exec, s[4:5]
	s_add_i32 s96, s96, 1
	s_cmp_eq_u32 s96, 4
	s_waitcnt lgkmcnt(0)
	s_barrier
	s_cbranch_scc1 .LBB0_928
	s_nop 0
	s_nop 0
	s_nop 0
	s_nop 0

; __device__ __forceinline__ void p0_phase(LAS unsigned char* lds, const Args& a, const int w0) {
;     ...
;     for (int it = gw; it < I_IN + 2 * I_SQ + I_PP; it += NGW) {
;         int r = it;
;         if (r < I_IN) { const int L = r / (52 * 16), q = r % (52 * 16), nb = q % 52, kb = q / 52;
;             tr_item64(a.in[8] + (size_t)L * DM * INW, INW, DM, win_src_col(2 * nb), win_src_col(2 * nb + 1), a.in[7] + L * DM, (bf16_t*)(ws + WS_WIN) + (size_t)L * INW * DM, nb * 64, kb * 64, scr, lane); continue; }
;         r -= I_IN;
;         if (r < 2 * I_SQ) { const int which = r / I_SQ; r %= I_SQ; const int L = r / 256, q = r % 256, nb = q & 15, kb = q >> 4;
;             tr_item64(a.in[which ? 12 : 11] + (size_t)L * DM * DM, DM, DM, nb * 64, nb * 64 + 32, nullptr, (bf16_t*)(ws + (which ? WS_WPG : WS_WOUT)) + (size_t)L * DM * DM, nb * 64, kb * 64, scr, lane); continue; }
.Ldw_w_loop:
	s_cmp_gt_u32 s15, 1151
	s_cbranch_scc1 .Ldw_w_end
	v_writelane_b32 v55, s15, 0
	v_writelane_b32 v55, s14, 1
	s_cmp_gt_u32 s15, 511
	s_cbranch_scc1 .Ldw_w_notout
	s_lshl_b32 s12, s14, 22
	s_add_u32 s8, s16, s12
	s_addc_u32 s9, s17, 0
	s_lshl_b32 s12, s14, 21
	s_add_u32 s12, s12, 0x1c00000
	s_add_u32 s12, s28, s12
	s_addc_u32 s13, s29, 0
	s_branch .Ldw_w_sq

; #define LAS __attribute__((address_space(3)))
; template <class T, class P> __device__ __forceinline__ T gld_nt(P p) { return __builtin_nontemporal_load((GAS const T*)p); }
; __device__ __forceinline__ unsigned pk2(float lo, float hi) { return pg8::cvt_pk_bf16(lo, hi); }
; __device__ __forceinline__ void tr_item64(const float* W, int N, int K, int src_a, int src_b, const float* g, bf16_t* WT, int dst_row0, int k0, LAS float* scr, int lane) {
;     const int sc = (lane < 32 ? src_a : src_b) + (lane & 31);
;     float v[64];
; #pragma unroll
;     for (int kk = 0; kk < 64; ++kk) v[kk] = gld_nt<float>(W + (size_t)(k0 + kk) * N + sc);
; #pragma unroll
;     for (int kk = 0; kk < 64; ++kk) scr[kk * 65 + lane] = g ? v[kk] * gld<float>(g + k0 + kk) : v[kk];
;     asm volatile("s_waitcnt lgkmcnt(0)" ::: "memory");
;     const int c = lane & 7;
; #pragma unroll
;     for (int j = 0; j < 8; ++j) { const int n = (lane >> 3) + 8 * j; const LAS float* sp = scr + (8 * c) * 65 + n;
;         u32x4 o; o.x = pk2(sp[0 * 65], sp[1 * 65]); o.y = pk2(sp[2 * 65], sp[3 * 65]); o.z = pk2(sp[4 * 65], sp[5 * 65]); o.w = pk2(sp[6 * 65], sp[7 * 65]);
;         gst<u32x4>(WT + (size_t)(dst_row0 + n) * K + k0 + 8 * c, o); }
;     asm volatile("s_waitcnt lgkmcnt(0)" ::: "memory");
; }
; __device__ __forceinline__ void p0_phase(LAS unsigned char* lds, const Args& a, const int w0) {
;     ...
;         { const int L = r / 64, q = r % 64, nb = q & 15, kb = q >> 4;
;             tr_item64(a.in[13] + (size_t)L * PLE * DM, DM, PLE, nb * 64, nb * 64 + 32, nullptr, (bf16_t*)(ws + WS_WPP) + (size_t)L * DM * PLE, nb * 64, kb * 64, scr, lane); }
.Ldw_w_pp:
	s_cmp_gt_u32 s14, 2
	s_cbranch_scc1 .Ldw_w_next
	s_add_i32 s15, s15, 0xfffffc00
	s_add_i32 s14, s14, 1
	s_lshl_b32 s12, s14, 20
	s_add_u32 s8, s26, s12
	s_addc_u32 s9, s27, 0
	s_lshl_b32 s12, s14, 19
	s_add_u32 s12, s12, 0x2c00000
	s_add_u32 s12, s28, s12
	s_addc_u32 s13, s29, 0
	s_and_b32 s10, s15, 15
	s_lshr_b32 s11, s15, 4
	s_lshl_b32 s11, s11, 17
	s_add_u32 s8, s8, s11
	s_addc_u32 s9, s9, 0
	s_lshl_b32 s11, s10, 8
	s_add_u32 s8, s8, s11
	s_addc_u32 s9, s9, 0
	s_lshl_b32 s10, s10, 15
	s_add_u32 s12, s12, s10
	s_addc_u32 s13, s13, 0
	s_lshr_b32 s11, s15, 4
	s_lshl_b32 s11, s11, 6
	s_add_u32 s12, s12, s11
	s_addc_u32 s13, s13, 0
	v_lshlrev_b32_e32 v52, 2, v54
	v_lshlrev_b32_e32 v53, 9, v54
	global_load_dword v4, v52, s[8:9] nt
	s_add_u32 s8, s8, 0x1000
	s_addc_u32 s9, s9, 0
	global_load_dword v5, v52, s[8:9] nt
	s_add_u32 s8, s8, 0x1000
	s_addc_u32 s9, s9, 0
	global_load_dword v6, v52, s[8:9] nt
	s_add_u32 s8, s8, 0x1000
	s_addc_u32 s9, s9, 0
	global_load_dword v7, v52, s[8:9] nt
	s_add_u32 s8, s8, 0x1000
	s_addc_u32 s9, s9, 0
	global_load_dword v8, v52, s[8:9] nt
	s_add_u32 s8, s8, 0x1000
	s_addc_u32 s9, s9, 0
	global_load_dword v9, v52, s[8:9] nt
	s_add_u32 s8, s8, 0x1000
	s_addc_u32 s9, s9, 0
	global_load_dword v10, v52, s[8:9] nt
	s_add_u32 s8, s8, 0x1000
	s_addc_u32 s9, s9, 0
	global_load_dword v11, v52, s[8:9] nt
	s_add_u32 s8, s8, 0x1000
	s_addc_u32 s9, s9, 0
	global_load_dword v12, v52, s[8:9] nt
	s_add_u32 s8, s8, 0x1000
	s_addc_u32 s9, s9, 0
	global_load_dword v13, v52, s[8:9] nt
	s_add_u32 s8, s8, 0x1000
	s_addc_u32 s9, s9, 0
	global_load_dword v14, v52, s[8:9] nt
	s_add_u32 s8, s8, 0x1000
	s_addc_u32 s9, s9, 0
	global_load_dword v15, v52, s[8:9] nt
	s_add_u32 s8, s8, 0x1000
	s_addc_u32 s9, s9, 0
	global_load_dword v16, v52, s[8:9] nt
	s_add_u32 s8, s8, 0x1000
	s_addc_u32 s9, s9, 0
	global_load_dword v17, v52, s[8:9] nt
	s_add_u32 s8, s8, 0x1000
	s_addc_u32 s9, s9, 0
	global_load_dword v18, v52, s[8:9] nt
	s_add_u32 s8, s8, 0x1000
	s_addc_u32 s9, s9, 0
	global_load_dword v19, v52, s[8:9] nt
	s_add_u32 s8, s8, 0x1000
	s_addc_u32 s9, s9, 0
	global_load_dword v20, v52, s[8:9] nt
	s_add_u32 s8, s8, 0x1000
	s_addc_u32 s9, s9, 0
	global_load_dword v21, v52, s[8:9] nt
	s_add_u32 s8, s8, 0x1000
	s_addc_u32 s9, s9, 0
	global_load_dword v22, v52, s[8:9] nt
	s_add_u32 s8, s8, 0x1000
	s_addc_u32 s9, s9, 0
	global_load_dword v23, v52, s[8:9] nt
	s_add_u32 s8, s8, 0x1000
	s_addc_u32 s9, s9, 0
	global_load_dword v24, v52, s[8:9] nt
	s_add_u32 s8, s8, 0x1000
	s_addc_u32 s9, s9, 0
	global_load_dword v25, v52, s[8:9] nt
	s_add_u32 s8, s8, 0x1000
	s_addc_u32 s9, s9, 0
	global_load_dword v26, v52, s[8:9] nt
	s_add_u32 s8, s8, 0x1000
	s_addc_u32 s9, s9, 0
	global_load_dword v27, v52, s[8:9] nt
	s_add_u32 s8, s8, 0x1000
	s_addc_u32 s9, s9, 0
	global_load_dword v28, v52, s[8:9] nt
	s_add_u32 s8, s8, 0x1000
	s_addc_u32 s9, s9, 0
	global_load_dword v29, v52, s[8:9] nt
	s_add_u32 s8, s8, 0x1000
	s_addc_u32 s9, s9, 0
	global_load_dword v30, v52, s[8:9] nt
	s_add_u32 s8, s8, 0x1000
	s_addc_u32 s9, s9, 0
	global_load_dword v31, v52, s[8:9] nt
	s_add_u32 s8, s8, 0x1000
	s_addc_u32 s9, s9, 0
	global_load_dword v32, v52, s[8:9] nt
	s_add_u32 s8, s8, 0x1000
	s_addc_u32 s9, s9, 0
	global_load_dword v33, v52, s[8:9] nt
	s_add_u32 s8, s8, 0x1000
	s_addc_u32 s9, s9, 0
	global_load_dword v34, v52, s[8:9] nt
	s_add_u32 s8, s8, 0x1000
	s_addc_u32 s9, s9, 0
	global_load_dword v35, v52, s[8:9] nt
	s_waitcnt vmcnt(24)
	v_cvt_pk_bf16_f32 v36, v4, v5
	v_cvt_pk_bf16_f32 v37, v6, v7
	v_cvt_pk_bf16_f32 v38, v8, v9
	v_cvt_pk_bf16_f32 v39, v10, v11
	s_waitcnt vmcnt(16)
	v_cvt_pk_bf16_f32 v40, v12, v13
	v_cvt_pk_bf16_f32 v41, v14, v15
	v_cvt_pk_bf16_f32 v42, v16, v17
	v_cvt_pk_bf16_f32 v43, v18, v19
	s_waitcnt vmcnt(8)
	v_cvt_pk_bf16_f32 v44, v20, v21
	v_cvt_pk_bf16_f32 v45, v22, v23
	v_cvt_pk_bf16_f32 v46, v24, v25
	v_cvt_pk_bf16_f32 v47, v26, v27
	s_waitcnt vmcnt(0)
	v_cvt_pk_bf16_f32 v48, v28, v29
	v_cvt_pk_bf16_f32 v49, v30, v31
	v_cvt_pk_bf16_f32 v50, v32, v33
	v_cvt_pk_bf16_f32 v51, v34, v35
	global_store_dwordx4 v53, v[36:39], s[12:13]
	global_store_dwordx4 v53, v[40:43], s[12:13] offset:16
	global_store_dwordx4 v53, v[44:47], s[12:13] offset:32
	global_store_dwordx4 v53, v[48:51], s[12:13] offset:48
.Ldw_w_next:
	v_readlane_b32 s15, v55, 0
	v_readlane_b32 s14, v55, 1
	s_mul_i32 s10, s24, 7
	s_add_i32 s15, s15, s10
	s_branch .Ldw_w_loop

; #define LAS __attribute__((address_space(3)))
; __device__ __forceinline__ u32x2 pk4(f32x4 a) { u32x2 w; w.x = pk2(a[0], a[1]); w.y = pk2(a[2], a[3]); return w; }
; __device__ __forceinline__ unsigned char* ka_ws() { return (unsigned char*)(GAS unsigned char*)ka_u64(128); }
;     __device__ __forceinline__ void small(f32x4 acc, int row, int col, int chunk) const {
;         unsigned char* ws = ka_ws(); const bf16_t* X0 = (const bf16_t*)(ws + WS_XB0); bf16_t* X1 = (bf16_t*)(ws + WS_XB1);
;         gst<u32x2>(X1 + (size_t)row * DM + col, pk4(bf4(gld<u32x2>(X0 + (size_t)row * DM + col)) + acc));
;     }
; template <class Epi>
; __device__ __forceinline__ void small_gemm(LAS unsigned char* lds, const bf16_t* A, const bf16_t* Bt, const Epi& E, const int w0) {
;     ...
;     for (int tile = blockIdx.x; tile < 256; tile += gridDim.x) {
;         const int rt = tile >> 4, ct = tile & 15, k0 = wid * 128;
;         bf16x8 af[2][4], bw[4][4];
; #pragma unroll
;         for (int i = 0; i < 2; ++i)
; #pragma unroll
;             for (int ks = 0; ks < 4; ++ks) af[i][ks] = gld<bf16x8>(A + (size_t)(rt * 32 + i * 16 + fr) * DM + k0 + ks * 32 + fq * 8);
; #pragma unroll
;         for (int j = 0; j < 4; ++j)
; #pragma unroll
;             for (int ks = 0; ks < 4; ++ks) bw[j][ks] = gld<bf16x8>(Bt + (size_t)(ct * 64 + j * 16 + fr) * DM + k0 + ks * 32 + fq * 8);
;         f32x4 acc[2][4];
; #pragma unroll
;         for (int i = 0; i < 2; ++i)
; #pragma unroll
;             for (int j = 0; j < 4; ++j) { acc[i][j] = (f32x4){0.f, 0.f, 0.f, 0.f};
; #pragma unroll
;                 for (int ks = 0; ks < 4; ++ks) acc[i][j] = __builtin_amdgcn_mfma_f32_16x16x32_bf16(bw[j][ks], af[i][ks], acc[i][j], 0, 0, 0); }
;         __syncthreads();
; #pragma unroll
;         for (int i = 0; i < 2; ++i)
; #pragma unroll
;             for (int j = 0; j < 4; ++j) *(LAS f32x4*)(lds + ((wid * 8 + i * 4 + j) * 64 + lane) * 16) = acc[i][j];
;         __syncthreads();
;         const int row = tid >> 4, c4 = tid & 15, til = (row >> 4) * 4 + (c4 >> 2), l = (row & 15) + 16 * (c4 & 3);
;         f32x4 sum = (f32x4){0.f, 0.f, 0.f, 0.f};
; #pragma unroll
;         for (int w = 0; w < 8; ++w) sum += *(LAS const f32x4*)(lds + ((w * 8 + til) * 64 + l) * 16);
;         E.small(sum, NPR + rt * 32 + row, ct * 64 + c4 * 4, ct);
.LBB0_777:
	s_and_b32 s28, s18, 0xffffffe0
	s_and_b32 s29, s19, 15
	v_or_b32_e32 v4, s28, v10
	v_lshl_or_b32 v192, s29, 17, v12
	v_ashrrev_i32_e32 v5, 31, v4
	v_lshl_add_u64 v[68:69], v[2:3], 0, v[192:193]
	v_or_b32_e32 v20, 16, v4
	v_lshlrev_b64 v[22:23], 11, v[4:5]
	v_add_co_u32_e32 v8, vcc, s49, v68
	v_add_co_u32_e64 v6, s[4:5], s22, v68
	v_add_co_u32_e64 v4, s[8:9], s36, v68
	v_addc_co_u32_e32 v9, vcc, 0, v69, vcc
	v_addc_co_u32_e64 v7, vcc, 0, v69, s[4:5]
	v_addc_co_u32_e64 v5, vcc, 0, v69, s[8:9]
	v_ashrrev_i32_e32 v21, 31, v20
	v_lshlrev_b64 v[24:25], 11, v[20:21]
	v_lshl_add_u64 v[70:71], v[0:1], 0, v[22:23]
	v_lshl_add_u64 v[72:73], v[0:1], 0, v[24:25]
	global_load_dwordx4 v[80:83], v[70:71], off
	global_load_dwordx4 v[96:99], v[72:73], off
	global_load_dwordx4 v[112:115], v[68:69], off
	global_load_dwordx4 v[128:131], v[8:9], off
	global_load_dwordx4 v[144:147], v[6:7], off
	global_load_dwordx4 v[160:163], v[4:5], off
	global_load_dwordx4 v[84:87], v[70:71], off offset:64
	global_load_dwordx4 v[100:103], v[72:73], off offset:64
	global_load_dwordx4 v[116:119], v[68:69], off offset:64
	global_load_dwordx4 v[132:135], v[8:9], off offset:64
	global_load_dwordx4 v[148:151], v[6:7], off offset:64
	global_load_dwordx4 v[164:167], v[4:5], off offset:64
	global_load_dwordx4 v[88:91], v[70:71], off offset:128
	global_load_dwordx4 v[104:107], v[72:73], off offset:128
	global_load_dwordx4 v[120:123], v[68:69], off offset:128
	global_load_dwordx4 v[136:139], v[8:9], off offset:128
	global_load_dwordx4 v[152:155], v[6:7], off offset:128
	global_load_dwordx4 v[168:171], v[4:5], off offset:128
	global_load_dwordx4 v[92:95], v[70:71], off offset:192
	global_load_dwordx4 v[108:111], v[72:73], off offset:192
	global_load_dwordx4 v[124:127], v[68:69], off offset:192
	global_load_dwordx4 v[140:143], v[8:9], off offset:192
	global_load_dwordx4 v[156:159], v[6:7], off offset:192
	global_load_dwordx4 v[172:175], v[4:5], off offset:192
	s_mov_b64 s[4:5], s[0:1]
	v_lshl_or_b32 v192, s29, 7, v15
	s_add_i32 s19, s19, s24
	s_add_i32 s18, s18, s37
	s_cmpk_lt_i32 s19, 0x100
	s_waitcnt vmcnt(18)
	v_mfma_f32_16x16x32_bf16 v[24:27], v[112:115], v[80:83], 0
	v_mfma_f32_16x16x32_bf16 v[16:19], v[112:115], v[96:99], 0
	v_mfma_f32_16x16x32_bf16 v[36:39], v[128:131], v[80:83], 0
	v_mfma_f32_16x16x32_bf16 v[32:35], v[128:131], v[96:99], 0
	v_mfma_f32_16x16x32_bf16 v[44:47], v[144:147], v[80:83], 0
	v_mfma_f32_16x16x32_bf16 v[40:43], v[144:147], v[96:99], 0
	v_mfma_f32_16x16x32_bf16 v[20:23], v[160:163], v[80:83], 0
	v_mfma_f32_16x16x32_bf16 v[28:31], v[160:163], v[96:99], 0
	s_waitcnt vmcnt(12)
	v_mfma_f32_16x16x32_bf16 v[24:27], v[116:119], v[84:87], v[24:27]
	v_mfma_f32_16x16x32_bf16 v[16:19], v[116:119], v[100:103], v[16:19]
	v_mfma_f32_16x16x32_bf16 v[36:39], v[132:135], v[84:87], v[36:39]
	v_mfma_f32_16x16x32_bf16 v[32:35], v[132:135], v[100:103], v[32:35]
	v_mfma_f32_16x16x32_bf16 v[44:47], v[148:151], v[84:87], v[44:47]
	v_mfma_f32_16x16x32_bf16 v[40:43], v[148:151], v[100:103], v[40:43]
	v_mfma_f32_16x16x32_bf16 v[20:23], v[164:167], v[84:87], v[20:23]
	v_mfma_f32_16x16x32_bf16 v[28:31], v[164:167], v[100:103], v[28:31]
	s_waitcnt vmcnt(6)
	v_add_u32_e32 v4, s28, v11
	v_ashrrev_i32_e32 v5, 31, v4
	v_mfma_f32_16x16x32_bf16 v[24:27], v[120:123], v[88:91], v[24:27]
	v_mfma_f32_16x16x32_bf16 v[16:19], v[120:123], v[104:107], v[16:19]
	v_mfma_f32_16x16x32_bf16 v[36:39], v[136:139], v[88:91], v[36:39]
	v_mfma_f32_16x16x32_bf16 v[32:35], v[136:139], v[104:107], v[32:35]
	v_mfma_f32_16x16x32_bf16 v[44:47], v[152:155], v[88:91], v[44:47]
	v_mfma_f32_16x16x32_bf16 v[40:43], v[152:155], v[104:107], v[40:43]
	v_mfma_f32_16x16x32_bf16 v[20:23], v[168:171], v[88:91], v[20:23]
	v_mfma_f32_16x16x32_bf16 v[28:31], v[168:171], v[104:107], v[28:31]
	s_waitcnt vmcnt(0)
	s_barrier
	v_mfma_f32_16x16x32_bf16 v[24:27], v[124:127], v[92:95], v[24:27]
	v_mfma_f32_16x16x32_bf16 v[16:19], v[124:127], v[108:111], v[16:19]
	v_mfma_f32_16x16x32_bf16 v[36:39], v[140:143], v[92:95], v[36:39]
	v_mfma_f32_16x16x32_bf16 v[32:35], v[140:143], v[108:111], v[32:35]
	v_mfma_f32_16x16x32_bf16 v[44:47], v[156:159], v[92:95], v[44:47]
	v_mfma_f32_16x16x32_bf16 v[20:23], v[172:175], v[92:95], v[20:23]
	v_mfma_f32_16x16x32_bf16 v[28:31], v[172:175], v[108:111], v[28:31]
	v_lshlrev_b64 v[48:49], 11, v[4:5]
	v_mfma_f32_16x16x32_bf16 v[4:7], v[156:159], v[108:111], v[40:43]
	s_nop 7
	s_nop 1
	ds_write_b128 v13, v[24:27]
	ds_write_b128 v13, v[16:19] offset:4096
	s_nop 0
	ds_write_b128 v13, v[36:39] offset:1024
	s_nop 0
	ds_write_b128 v13, v[44:47] offset:2048
	ds_write_b128 v13, v[20:23] offset:3072
	ds_write_b128 v13, v[32:35] offset:5120
	ds_write_b128 v13, v[4:7] offset:6144
	ds_write_b128 v13, v[28:31] offset:7168
	s_waitcnt lgkmcnt(0)
	s_barrier
	ds_read_b128 v[4:7], v14
	ds_read_b128 v[16:19], v14 offset:8192
	ds_read_b128 v[20:23], v14 offset:16384
	ds_read_b128 v[24:27], v14 offset:24576
	ds_read_b128 v[28:31], v14 offset:32768
	ds_read_b128 v[32:35], v14 offset:40960
	ds_read_b128 v[36:39], v14 offset:49152
	ds_read_b128 v[40:43], v14 offset:57344
	s_load_dwordx2 s[4:5], s[4:5], 0x80
	s_waitcnt lgkmcnt(0)
	v_pk_add_f32 v[4:5], v[4:5], 0 op_sel_hi:[1,0]
	v_pk_add_f32 v[6:7], v[6:7], 0 op_sel_hi:[1,0]
	v_pk_add_f32 v[4:5], v[4:5], v[16:17]
	v_pk_add_f32 v[6:7], v[6:7], v[18:19]
	v_lshl_add_u64 v[8:9], s[4:5], 0, v[48:49]
	v_lshl_add_u64 v[8:9], v[8:9], 0, v[192:193]
	v_add_co_u32_e32 v44, vcc, s45, v8
	v_pk_add_f32 v[4:5], v[4:5], v[20:21]
	s_nop 0
	v_addc_co_u32_e32 v45, vcc, 0, v9, vcc
	global_load_dwordx2 v[44:45], v[44:45], off
	v_pk_add_f32 v[6:7], v[6:7], v[22:23]
	v_pk_add_f32 v[4:5], v[4:5], v[24:25]
	v_pk_add_f32 v[6:7], v[6:7], v[26:27]
	v_pk_add_f32 v[4:5], v[4:5], v[28:29]
	v_pk_add_f32 v[6:7], v[6:7], v[30:31]
	v_pk_add_f32 v[4:5], v[4:5], v[32:33]
	v_pk_add_f32 v[6:7], v[6:7], v[34:35]
	v_pk_add_f32 v[4:5], v[4:5], v[36:37]
	v_add_co_u32_e32 v8, vcc, 0xb200000, v8
	v_pk_add_f32 v[6:7], v[6:7], v[38:39]
	v_pk_add_f32 v[4:5], v[4:5], v[40:41]
	v_addc_co_u32_e32 v9, vcc, 0, v9, vcc
	v_pk_add_f32 v[6:7], v[6:7], v[42:43]
	s_waitcnt vmcnt(0)
	v_lshlrev_b32_e32 v16, 16, v44
	v_and_b32_e32 v17, 0xffff0000, v44
	v_lshlrev_b32_e32 v18, 16, v45
	v_and_b32_e32 v19, 0xffff0000, v45
	v_pk_add_f32 v[4:5], v[4:5], v[16:17]
	v_pk_add_f32 v[6:7], v[6:7], v[18:19]
	v_cvt_pk_bf16_f32 v4, v4, v5
	s_nop 0
	v_cvt_pk_bf16_f32 v5, v6, v7
	global_store_dwordx2 v[8:9], v[4:5], off
	s_cbranch_scc1 .LBB0_777
	s_branch .LBB0_750
